# static s_setprio 1 for waves 0-3 during the attention phase (one raise at phase entry, reset at exit)
# speedup vs baseline: 1.0043x; 1.0043x over previous
.LBB0_1483:
	s_or_b64 exec, exec, s[0:1]
	s_waitcnt vmcnt(0)
	v_mov_b32_e32 v7, v228
	s_barrier
	v_mov_b32_e32 v1, 0
	v_readfirstlane_b32 s6, v7
	s_ashr_i32 s12, s6, 6
	s_add_u32 s0, s90, 0x23ab67fc
	s_addc_u32 s1, s91, 0
	v_writelane_b32 v250, s0, 11
	s_lshl_b32 s14, s12, 5
	v_and_b32_e32 v135, 31, v7
	v_writelane_b32 v250, s1, 12
	s_add_u32 s0, s90, 0x19a00800
	s_addc_u32 s1, s91, 0
	v_writelane_b32 v250, s0, 13
	v_ashrrev_i32_e32 v2, 3, v7
	v_bfe_u32 v8, v7, 5, 1
	v_writelane_b32 v250, s1, 14
	s_and_b32 s0, s14, 0xffffffc0
	v_writelane_b32 v250, s0, 15
	s_add_u32 s0, s90, 0x1da40800
	v_writelane_b32 v250, s0, 16
	s_addc_u32 s0, s91, 0
	v_writelane_b32 v250, s0, 17
	s_add_u32 s0, s90, 0x1ea40800
	v_writelane_b32 v250, s0, 18
	s_addc_u32 s0, s91, 0
	v_writelane_b32 v250, s0, 19
	s_movk_i32 s0, 0x90
	v_mul_lo_u32 v9, v2, s0
	v_mad_u32_u24 v160, v135, s0, 0
	s_add_u32 s0, s90, 0x98c0800
	s_addc_u32 s1, s91, 0
	s_add_u32 s8, s90, 0xd900800
	v_writelane_b32 v250, s8, 20
	s_addc_u32 s8, s91, 0
	v_writelane_b32 v250, s8, 21
	s_add_u32 s8, s90, 0x11900800
	v_writelane_b32 v250, s8, 22
	s_addc_u32 s8, s91, 0
	v_writelane_b32 v250, s8, 23
	s_add_u32 s8, s90, 0x237b1800
	v_writelane_b32 v250, s8, 24
	s_addc_u32 s8, s91, 0
	v_writelane_b32 v250, s8, 25
	s_add_u32 s8, s90, 0x23ab5800
	v_writelane_b32 v250, s8, 26
	s_addc_u32 s8, s91, 0
	v_writelane_b32 v250, s8, 27
	s_add_u32 s8, s90, 0x239b1800
	v_lshlrev_b32_e32 v136, 2, v8
	v_writelane_b32 v250, s8, 28
	s_addc_u32 s8, s91, 0
	v_ashrrev_i32_e32 v3, 31, v2
	v_writelane_b32 v250, s8, 29
	v_cmp_gt_u32_e64 s[8:9], v136, v135
	v_lshlrev_b64 v[4:5], 7, v[2:3]
	v_mul_lo_u32 v11, v2, 48
	v_lshlrev_b64 v[140:141], 9, v[2:3]
	v_writelane_b32 v251, s8, 46
	v_or_b32_e32 v2, 2, v136
	v_cmp_gt_u32_e64 s[16:17], v2, v135
	v_writelane_b32 v251, s9, 47
	v_or_b32_e32 v2, 3, v136
	v_writelane_b32 v251, s16, 48
	v_and_b32_e32 v6, 7, v7
	v_lshlrev_b32_e32 v10, 4, v6
	v_writelane_b32 v251, s17, 49
	v_cmp_gt_u32_e64 s[16:17], v2, v135
	v_or_b32_e32 v2, 8, v136
	v_add3_u32 v137, v9, v10, 0
	v_writelane_b32 v251, s16, 54
	v_lshrrev_b32_e32 v9, 2, v7
	v_and_b32_e32 v134, 63, v7
	v_writelane_b32 v251, s17, 55
	v_cmp_gt_u32_e64 s[16:17], v2, v135
	v_or_b32_e32 v2, 9, v136
	v_cmp_eq_u32_e64 s[2:3], 0, v7
	v_writelane_b32 v251, s16, 57
	v_cmp_lt_i32_e64 s[4:5], 63, v7
	v_lshlrev_b32_e32 v139, 2, v7
	v_writelane_b32 v251, s17, 58
	v_cmp_gt_u32_e64 s[16:17], v2, v135
	v_or_b32_e32 v2, 10, v136
	v_and_or_b32 v9, v9, 3, v136
	v_writelane_b32 v251, s16, 59
	v_and_b32_e32 v7, 16, v7
	s_cmp_lt_u32 s6, 64
	v_writelane_b32 v251, s17, 60
	v_cmp_gt_u32_e64 s[16:17], v2, v135
	v_or_b32_e32 v2, 11, v136
	v_mul_u32_u24_e32 v9, 0xc0, v9
	v_writelane_b32 v251, s16, 52
	v_and_or_b32 v7, v139, 12, v7
	s_cselect_b64 s[10:11], -1, 0
	v_writelane_b32 v251, s17, 53
	v_cmp_gt_u32_e64 s[16:17], v2, v135
	v_or_b32_e32 v2, 16, v136
	s_and_b32 s6, s6, 0xc0
	v_writelane_b32 v251, s16, 61
	v_lshlrev_b32_e32 v0, 3, v6
	v_lshlrev_b32_e32 v6, 3, v8
	v_writelane_b32 v251, s17, 62
	v_cmp_gt_u32_e64 s[16:17], v2, v135
	v_or_b32_e32 v2, 17, v136
	v_lshl_or_b32 v7, v7, 1, v9
	v_writelane_b32 v250, s16, 7
	v_lshlrev_b32_e32 v161, 4, v8
	s_cmp_lt_i32 s12, 4
	v_writelane_b32 v250, s17, 8
	v_cmp_gt_u32_e64 s[16:17], v2, v135
	v_or_b32_e32 v2, 18, v136
	v_cmp_gt_u32_e64 s[26:27], v2, v135
	v_or_b32_e32 v2, 19, v136
	v_cmp_gt_u32_e64 s[28:29], v2, v135
	v_or_b32_e32 v2, 24, v136
	v_cmp_gt_u32_e64 s[30:31], v2, v135
	v_or_b32_e32 v2, 25, v136
	v_writelane_b32 v250, s16, 9
	v_cmp_gt_u32_e64 s[34:35], v2, v135
	v_or_b32_e32 v2, 26, v136
	v_writelane_b32 v250, s17, 10
	v_cmp_gt_u32_e64 s[36:37], v2, v135
	v_or_b32_e32 v2, 27, v136
	s_mov_b32 s7, 0
	v_add_u32_e32 v162, 0, v7
	v_lshlrev_b32_e32 v138, 6, v134
	v_add_u32_e32 v163, 0, v161
	v_or_b32_e32 v142, 0x10000, v135
	v_cmp_lt_u32_e64 s[8:9], v136, v135
	v_cmp_gt_u32_e64 s[38:39], v2, v135
	v_mov_b32_e32 v143, v1
	v_writelane_b32 v250, s6, 30
	s_cselect_b64 s[12:13], -1, 0
	v_and_or_b32 v164, s14, 32, v135
	v_or_b32_e32 v165, 0xf40, v136
	v_or_b32_e32 v166, 0xf80, v136
	v_lshlrev_b64 v[144:145], 1, v[4:5]
	v_add_u32_e32 v167, v137, v11
	s_mov_b32 s16, 0x41000000
	v_mov_b32_e32 v168, 0x260
	v_mov_b32_e32 v169, 0x41c00000
	s_mov_b32 s17, 0xc1c00000
	v_mov_b32_e32 v170, 0x23ab5000
	v_mov_b32_e32 v171, 0x4000
	v_lshlrev_b32_e32 v146, 1, v0
	v_lshlrev_b32_e32 v148, 1, v6
	v_mov_b32_e32 v172, 0xff800000
	v_writelane_b32 v250, s14, 31
	v_readfirstlane_b32 s100, v228
	s_cmpk_lt_u32 s100, 0x100
	s_cbranch_scc0 .Lp3prio_skip
	s_setprio 1
.Lp3prio_skip:
	s_branch .LBB0_1486
.LBB0_1484:
	s_mov_b64 s[14:15], 0

.LBB0_1628:
	s_setprio 0
	v_readlane_b32 s68, v251, 20
	v_readlane_b32 s69, v251, 21
	s_waitcnt lgkmcnt(0)
	s_barrier
	s_and_saveexec_b64 s[2:3], s[68:69]
	v_readlane_b32 s76, v251, 50
	v_readlane_b32 s77, v251, 51
	v_readlane_b32 s77, v251, 19
	v_readlane_b32 s70, v251, 56
	s_cbranch_execz .LBB0_1638
	v_readlane_b32 s4, v251, 0
	v_readlane_b32 s5, v251, 1
	buffer_wbl2 sc1
	s_waitcnt vmcnt(0)
	s_load_dwordx2 s[4:5], s[4:5], 0x58
	v_mov_b32_e32 v2, 0
	s_mov_b64 s[6:7], exec
	v_mbcnt_lo_u32_b32 v1, s6, 0
	v_mbcnt_hi_u32_b32 v1, s7, v1
	s_waitcnt lgkmcnt(0)
	global_load_dword v0, v2, s[4:5] offset:40
	v_cmp_eq_u32_e32 vcc, 0, v1
	s_and_saveexec_b64 s[8:9], vcc
	s_cbranch_execz .LBB0_1631
	s_bcnt1_i32_b64 s6, s[6:7]
	v_mov_b32_e32 v3, s6
	global_atomic_add v3, v2, v3, s[4:5] offset:32 sc0
